# scan: filler rows of the matvec A operand read the a / w.r rows (same address as rows 0/1, broadcast) instead of a separate zero block: 3-way LDS bank conflict on the X reads becomes 2-way
# baseline (speedup 1.0000x reference)
.LBB0_109:
	s_andn2_b64 vcc, exec, s[4:5]
	s_cbranch_vccnz .LBB0_490
	s_cmp_lt_i32 s58, 12
	s_mov_b64 s[4:5], -1
	s_cbranch_scc1 .LBB0_457
	s_cmp_lt_i32 s58, 13
	s_cbranch_scc1 .LBB0_273
	s_cmp_gt_i32 s58, 13
	s_cbranch_scc0 .LBB0_201
	v_writelane_b32 v255, s58, 30
	s_mov_b32 s40, -1
	s_mov_b32 s22, s72
	v_writelane_b32 v255, s59, 31
	s_mov_b32 s10, 25
	v_readlane_b32 s4, v255, 3
	v_readlane_b32 s5, v255, 4
	v_readlane_b32 s6, v255, 5
	v_readlane_b32 s7, v255, 6
	s_mov_b32 s8, 26
	s_mov_b32 s4, 27
	s_cmpk_gt_i32 s22, 0xff
	s_cbranch_scc1 .LBB0_200
	s_ashr_i32 s11, s10, 31
	s_lshl_b64 s[10:11], s[10:11], 3
	v_readlane_b32 s0, v255, 8
	v_readlane_b32 s1, v255, 9
	s_add_u32 s10, s0, s10
	s_addc_u32 s11, s1, s11
	s_ashr_i32 s9, s8, 31
	s_lshl_b64 s[8:9], s[8:9], 3
	s_add_u32 s8, s0, s8
	s_addc_u32 s9, s1, s9
	s_ashr_i32 s5, s4, 31
	s_lshl_b64 s[4:5], s[4:5], 3
	s_add_u32 s4, s0, s4
	s_addc_u32 s5, s1, s5
	s_add_u32 s90, s6, 0x1c600000
	s_addc_u32 s91, s7, 0
	s_add_u32 s92, s6, 0x20600000
	s_addc_u32 s93, s7, 0
	s_add_u32 s94, s6, 0x24600000
	s_load_dwordx2 s[84:85], s[10:11], 0x0
	s_load_dwordx2 s[86:87], s[8:9], 0x0
	s_load_dwordx2 s[88:89], s[4:5], 0x0
	v_mbcnt_lo_u32_b32 v0, s40, 0
	s_addc_u32 s95, s7, 0
	s_and_b32 s8, s22, 1
	v_mbcnt_hi_u32_b32 v0, s40, v0
	v_readlane_b32 s0, v254, 4
	s_cmp_eq_u32 s8, 0
	s_movk_i32 s4, 0x120
	v_add_u32_e32 v106, s0, v0
	s_cselect_b64 s[52:53], -1, 0
	v_ashrrev_i32_e32 v2, 6, v106
	v_and_b32_e32 v3, 15, v0
	v_cmp_gt_i32_e64 s[72:73], s4, v106
	s_and_b64 s[4:5], s[52:53], exec
	v_cmp_gt_i32_e32 vcc, 4, v2
	v_lshl_or_b32 v108, v2, 4, v3
	v_and_b32_e32 v2, 1, v0
	s_mov_b32 s4, 0x8600000
	v_cmp_eq_u32_e64 s[40:41], 0, v2
	v_cmp_eq_u32_e64 s[42:43], 1, v2
	v_cmp_gt_u32_e64 s[44:45], 2, v2
	v_mov_b32_e32 v2, 0x80
	s_cselect_b32 s4, 0x4600000, s4
	s_mov_b32 s5, 0xc600000
	v_cndmask_b32_e64 v109, 0, v2, s[44:45]
	v_lshrrev_b32_e32 v2, 1, v0
	s_cselect_b32 s5, s5, 0x10600000
	s_add_u32 s96, s6, s4
	v_and_b32_e32 v110, 24, v2
	v_add_u32_e32 v2, 0xffffff00, v106
	s_addc_u32 s97, s7, 0
	v_ashrrev_i32_e32 v111, 3, v2
	v_and_b32_e32 v3, 7, v0
	s_add_u32 s4, s6, s5
	v_lshlrev_b32_e32 v112, 3, v3
	v_lshlrev_b32_e32 v116, 2, v3
	v_cmp_eq_u32_e64 s[50:51], 0, v3
	v_lshlrev_b32_e32 v8, 8, v111
	v_lshlrev_b32_e32 v3, 5, v3
	v_readlane_b32 s0, v254, 61
	s_addc_u32 s5, s7, 0
	s_lshl_b32 s8, s8, 21
	v_and_b32_e32 v107, 48, v0
	v_and_b32_e32 v6, 63, v0
	v_and_b32_e32 v0, 56, v0
	v_add3_u32 v117, s0, v8, v3
	v_readlane_b32 s0, v254, 62
	s_add_u32 s6, s6, s8
	v_lshl_add_u32 v113, v2, 2, s24
	v_sub_u32_e32 v4, 0xfff, v111
	v_and_b32_e32 v114, -8, v2
	v_cmp_eq_u32_e64 s[48:49], 56, v0
	v_and_b32_e32 v0, 0xffffffc0, v2
	v_add_u32_e32 v2, 0xfe0, v111
	v_sub_u32_e32 v7, 31, v111
	v_add3_u32 v118, s0, v8, v3
	v_readlane_b32 s0, v254, 63
	s_addc_u32 s7, s7, 0
	v_lshlrev_b32_e32 v5, 6, v111
	v_add3_u32 v119, s0, v8, v3
	v_cndmask_b32_e64 v78, v4, v111, s[52:53]
	s_add_u32 s0, s6, 0x29e00000
	v_cndmask_b32_e64 v80, v7, v2, s[52:53]
	v_cmp_eq_u32_e64 s[44:45], 0, v107
	v_lshlrev_b32_e32 v115, 5, v111
	s_addc_u32 s1, s7, 0
	v_lshlrev_b32_e32 v120, 1, v109
	v_mul_u32_u24_e32 v121, 3, v109
	v_lshlrev_b32_e32 v122, 2, v109
	v_mul_u32_u24_e32 v123, 5, v109
	v_mul_u32_u24_e32 v124, 6, v109
	v_mul_u32_u24_e32 v125, 7, v109
	v_lshlrev_b32_e32 v126, 3, v109
	v_mul_u32_u24_e32 v127, 9, v109
	v_mul_u32_u24_e32 v128, 10, v109
	v_mul_u32_u24_e32 v129, 11, v109
	v_mul_u32_u24_e32 v130, 12, v109
	v_mul_u32_u24_e32 v131, 13, v109
	v_mul_u32_u24_e32 v132, 14, v109
	v_mul_u32_u24_e32 v133, 15, v109
	v_lshlrev_b32_e32 v134, 4, v109
	v_mul_u32_u24_e32 v135, 17, v109
	v_mul_u32_u24_e32 v136, 18, v109
	v_mul_u32_u24_e32 v137, 19, v109
	v_mul_u32_u24_e32 v138, 20, v109
	v_mul_u32_u24_e32 v139, 21, v109
	v_mul_u32_u24_e32 v140, 22, v109
	v_mul_u32_u24_e32 v141, 23, v109
	v_mul_u32_u24_e32 v142, 24, v109
	v_mul_u32_u24_e32 v143, 25, v109
	v_mul_u32_u24_e32 v144, 26, v109
	v_mul_u32_u24_e32 v145, 27, v109
	v_mul_u32_u24_e32 v148, 28, v109
	v_mul_u32_u24_e32 v149, 29, v109
	v_mul_u32_u24_e32 v150, 30, v109
	v_mul_u32_u24_e32 v151, 31, v109
	v_ashrrev_i32_e32 v79, 31, v78
	v_cmp_gt_u32_e64 s[54:55], 8, v6
	v_cmp_gt_u32_e64 s[56:57], 16, v6
	v_cmp_gt_u32_e64 s[58:59], 32, v6
	v_ashrrev_i32_e32 v81, 31, v80
	v_lshlrev_b32_e32 v152, 7, v111
	v_sub_u32_e32 v153, 0xfdf, v111
	v_lshlrev_b32_e32 v154, 2, v5
	v_lshlrev_b32_e32 v155, 2, v0
	s_branch .LBB0_117
